# P7: odd XCDs start the three-segment branch GEMM ~9 us later so their gate-tile load bursts fall into the even XCDs' K-loops and vice versa
# baseline (speedup 1.0000x reference)
.LBB0_1648:
	s_cmp_ge_i32 s1, s80
	s_cselect_b64 s[10:11], -1, 0
	s_and_b64 s[6:7], s[10:11], s[6:7]
	s_andn2_b64 vcc, exec, s[6:7]
	s_cbranch_vccnz .LBB0_1746
	s_getreg_b32 s98, hwreg(HW_REG_XCC_ID, 0, 4)
	s_and_b32 s98, s98, 1
	s_cmp_eq_u32 s98, 0
	s_cbranch_scc1 .Lp7_nodelay
	s_sleep 127
	s_sleep 127
.Lp7_nodelay:
	s_mov_b64 s[8:9], s[78:79]
	s_movk_i32 s1, 0x400
	s_movk_i32 s6, 0x200
	s_movk_i32 s7, 0x4000
	s_ashr_i32 s12, s7, 31
	s_lshr_b32 s12, s12, 24
	s_add_i32 s7, s7, s12
	s_ashr_i32 s48, s7, 8
	s_ashr_i32 s7, s1, 31
	s_lshr_b32 s7, s7, 24
	s_add_i32 s1, s1, s7
	s_ashr_i32 s1, s1, 8
	s_mul_i32 s12, s1, s48
	s_waitcnt lgkmcnt(0)
	v_readlane_b32 s14, v249, 10
	v_mov_b32_e32 v12, v220
	s_cmp_lt_i32 s14, s12
	s_cselect_b64 s[24:25], -1, 0
	s_cmp_ge_i32 s14, s12
	v_readfirstlane_b32 s13, v12
	v_readlane_b32 s15, v249, 11
	s_cbranch_scc1 .LBB0_1655
	s_ashr_i32 s7, s12, 31
	s_lshr_b32 s7, s7, 29
	s_add_i32 s7, s12, s7
	s_ashr_i32 s30, s7, 3
	s_and_b32 s7, s7, -8
	s_sub_i32 s31, s12, s7
	s_add_i32 s17, s30, 1
	v_readlane_b32 s7, v250, 11
	s_cmp_ge_i32 s7, s31
	s_mov_b64 s[14:15], -1
	s_cbranch_scc0 .LBB0_1652
	v_readlane_b32 s14, v250, 11
	s_sub_i32 s14, s14, s31
	s_mul_i32 s7, s17, s31
	s_mul_i32 s14, s14, s30
	s_add_i32 s7, s14, s7
	s_mov_b64 s[14:15], 0
